# GEMM main loop: one static s_setprio 1 for waves 4-7 before the loop, all per-segment priority flips removed (strategy lever 4), on top of v86
# baseline (speedup 1.0000x reference)
.LBB0_2001:
	s_add_u32 s11, s24, 0x100
	s_addc_u32 s71, s25, 0
	s_add_u32 s2, s72, 0x80
	v_mov_b32_e32 v2, 0
	s_addc_u32 s3, s73, 0
	v_mov_b32_e32 v3, v2
	v_mov_b32_e32 v4, v2
	v_mov_b32_e32 v5, v2
	v_mov_b32_e32 v6, v2
	v_mov_b32_e32 v7, v2
	v_mov_b32_e32 v8, v2
	v_mov_b32_e32 v9, v2
	v_mov_b32_e32 v18, v2
	v_mov_b32_e32 v19, v2
	v_mov_b32_e32 v20, v2
	v_mov_b32_e32 v21, v2
	v_mov_b32_e32 v22, v2
	v_mov_b32_e32 v23, v2
	v_mov_b32_e32 v24, v2
	v_mov_b32_e32 v25, v2
	v_mov_b32_e32 v34, v2
	v_mov_b32_e32 v35, v2
	v_mov_b32_e32 v36, v2
	v_mov_b32_e32 v37, v2
	v_mov_b32_e32 v46, v2
	v_mov_b32_e32 v47, v2
	v_mov_b32_e32 v48, v2
	v_mov_b32_e32 v49, v2
	v_mov_b32_e32 v58, v2
	v_mov_b32_e32 v59, v2
	v_mov_b32_e32 v60, v2
	v_mov_b32_e32 v61, v2
	v_mov_b32_e32 v62, v2
	v_mov_b32_e32 v63, v2
	v_mov_b32_e32 v64, v2
	v_mov_b32_e32 v65, v2
	v_mov_b32_e32 v10, v2
	v_mov_b32_e32 v11, v2
	v_mov_b32_e32 v12, v2
	v_mov_b32_e32 v13, v2
	v_mov_b32_e32 v14, v2
	v_mov_b32_e32 v15, v2
	v_mov_b32_e32 v16, v2
	v_mov_b32_e32 v17, v2
	v_mov_b32_e32 v26, v2
	v_mov_b32_e32 v27, v2
	v_mov_b32_e32 v28, v2
	v_mov_b32_e32 v29, v2
	v_mov_b32_e32 v30, v2
	v_mov_b32_e32 v31, v2
	v_mov_b32_e32 v32, v2
	v_mov_b32_e32 v33, v2
	v_mov_b32_e32 v38, v2
	v_mov_b32_e32 v39, v2
	v_mov_b32_e32 v40, v2
	v_mov_b32_e32 v41, v2
	v_mov_b32_e32 v42, v2
	v_mov_b32_e32 v43, v2
	v_mov_b32_e32 v44, v2
	v_mov_b32_e32 v45, v2
	v_mov_b32_e32 v50, v2
	v_mov_b32_e32 v51, v2
	v_mov_b32_e32 v52, v2
	v_mov_b32_e32 v53, v2
	v_mov_b32_e32 v54, v2
	v_mov_b32_e32 v55, v2
	v_mov_b32_e32 v56, v2
	v_mov_b32_e32 v57, v2
	v_mov_b32_e32 v74, v2
	v_mov_b32_e32 v75, v2
	v_mov_b32_e32 v76, v2
	v_mov_b32_e32 v77, v2
	v_mov_b32_e32 v78, v2
	v_mov_b32_e32 v79, v2
	v_mov_b32_e32 v80, v2
	v_mov_b32_e32 v81, v2
	v_mov_b32_e32 v90, v2
	v_mov_b32_e32 v91, v2
	v_mov_b32_e32 v92, v2
	v_mov_b32_e32 v93, v2
	v_mov_b32_e32 v94, v2
	v_mov_b32_e32 v95, v2
	v_mov_b32_e32 v96, v2
	v_mov_b32_e32 v97, v2
	v_mov_b32_e32 v106, v2
	v_mov_b32_e32 v107, v2
	v_mov_b32_e32 v108, v2
	v_mov_b32_e32 v109, v2
	v_mov_b32_e32 v110, v2
	v_mov_b32_e32 v111, v2
	v_mov_b32_e32 v112, v2
	v_mov_b32_e32 v113, v2
	v_mov_b32_e32 v126, v2
	v_mov_b32_e32 v127, v2
	v_mov_b32_e32 v128, v2
	v_mov_b32_e32 v129, v2
	v_mov_b32_e32 v114, v2
	v_mov_b32_e32 v115, v2
	v_mov_b32_e32 v116, v2
	v_mov_b32_e32 v117, v2
	v_mov_b32_e32 v66, v2
	v_mov_b32_e32 v67, v2
	v_mov_b32_e32 v68, v2
	v_mov_b32_e32 v69, v2
	v_mov_b32_e32 v70, v2
	v_mov_b32_e32 v71, v2
	v_mov_b32_e32 v72, v2
	v_mov_b32_e32 v73, v2
	v_mov_b32_e32 v82, v2
	v_mov_b32_e32 v83, v2
	v_mov_b32_e32 v84, v2
	v_mov_b32_e32 v85, v2
	v_mov_b32_e32 v86, v2
	v_mov_b32_e32 v87, v2
	v_mov_b32_e32 v88, v2
	v_mov_b32_e32 v89, v2
	v_mov_b32_e32 v98, v2
	v_mov_b32_e32 v99, v2
	v_mov_b32_e32 v100, v2
	v_mov_b32_e32 v101, v2
	v_mov_b32_e32 v102, v2
	v_mov_b32_e32 v103, v2
	v_mov_b32_e32 v104, v2
	v_mov_b32_e32 v105, v2
	v_mov_b32_e32 v118, v2
	v_mov_b32_e32 v119, v2
	v_mov_b32_e32 v120, v2
	v_mov_b32_e32 v121, v2
	v_mov_b32_e32 v122, v2
	v_mov_b32_e32 v123, v2
	v_mov_b32_e32 v124, v2
	v_mov_b32_e32 v125, v2
	v_readlane_b32 s72, v251, 0
	s_cmp_lt_u32 s72, 4
	s_cbranch_scc1 .Lgp_older
	s_setprio 1
.Lgp_older:
.LBB0_2002:
	s_add_i32 s72, s51, 2
	s_add_u32 s24, s2, 0x80
	s_addc_u32 s25, s3, 0
	s_add_i32 s73, 0, 0x10000
	s_cmp_eq_u32 s31, s51
	s_cselect_b32 s25, s45, s25
	s_cselect_b32 s24, s44, s24
	s_cselect_b32 vcc_hi, s39, s71
	s_cselect_b32 vcc_lo, s38, s11
	s_add_i32 s51, 0, 0x14000
	v_add_u32_e32 v154, s73, v162
	v_add_u32_e32 v180, s51, v162
	ds_read_b128 v[130:133], v154
	ds_read_b128 v[134:137], v154 offset:1024
	ds_read_b128 v[150:153], v154 offset:2048
	ds_read_b128 v[154:157], v154 offset:3072
	ds_read_b128 v[168:171], v180
	ds_read_b128 v[172:175], v180 offset:1024
	ds_read_b128 v[176:179], v180 offset:2048
	ds_read_b128 v[180:183], v180 offset:3072
	v_lshl_add_u64 v[200:201], s[2:3], 0, v[148:149]
	s_add_i32 m0, s61, 0xc000
	ds_read_b128 v[184:187], v167
	ds_read_b128 v[188:191], v167 offset:1024
	ds_read_b128 v[192:195], v167 offset:2048
	ds_read_b128 v[196:199], v167 offset:3072
	ds_read_b128 v[220:223], v167 offset:4096
	ds_read_b128 v[224:227], v167 offset:5120
	ds_read_b128 v[228:231], v167 offset:6144
	ds_read_b128 v[232:235], v167 offset:7168
	global_load_lds_dwordx4 v[200:201], off
	v_lshl_add_u64 v[200:201], s[2:3], 0, v[146:147]
	s_add_i32 m0, s61, 0xe000
	s_nop 0
	global_load_lds_dwordx4 v[200:201], off
	s_waitcnt vmcnt(8)
	s_waitcnt lgkmcnt(0)
	s_barrier
	s_waitcnt lgkmcnt(0)
	v_mfma_f32_16x16x32_bf16 v[122:125], v[130:133], v[184:187], v[122:125]
	v_mfma_f32_16x16x32_bf16 v[118:121], v[150:153], v[184:187], v[118:121]
	v_mfma_f32_16x16x32_bf16 v[102:105], v[130:133], v[192:195], v[102:105]
	v_mfma_f32_16x16x32_bf16 v[98:101], v[150:153], v[192:195], v[98:101]
	v_mfma_f32_16x16x32_bf16 v[86:89], v[130:133], v[220:223], v[86:89]
	v_mfma_f32_16x16x32_bf16 v[82:85], v[150:153], v[220:223], v[82:85]
	v_mfma_f32_16x16x32_bf16 v[70:73], v[130:133], v[228:231], v[70:73]
	v_mfma_f32_16x16x32_bf16 v[66:69], v[150:153], v[228:231], v[66:69]
	v_mfma_f32_16x16x32_bf16 v[122:125], v[134:137], v[188:191], v[122:125]
	v_mfma_f32_16x16x32_bf16 v[118:121], v[154:157], v[188:191], v[118:121]
	v_mfma_f32_16x16x32_bf16 v[102:105], v[134:137], v[196:199], v[102:105]
	v_mfma_f32_16x16x32_bf16 v[98:101], v[154:157], v[196:199], v[98:101]
	v_mfma_f32_16x16x32_bf16 v[86:89], v[134:137], v[224:227], v[86:89]
	v_mfma_f32_16x16x32_bf16 v[82:85], v[154:157], v[224:227], v[82:85]
	v_mfma_f32_16x16x32_bf16 v[70:73], v[134:137], v[232:235], v[70:73]
	v_mfma_f32_16x16x32_bf16 v[66:69], v[154:157], v[232:235], v[66:69]
	v_mfma_f32_16x16x32_bf16 v[114:117], v[168:171], v[184:187], v[114:117]
	v_mfma_f32_16x16x32_bf16 v[126:129], v[176:179], v[184:187], v[126:129]
	v_mfma_f32_16x16x32_bf16 v[110:113], v[168:171], v[192:195], v[110:113]
	v_mfma_f32_16x16x32_bf16 v[106:109], v[176:179], v[192:195], v[106:109]
	v_mfma_f32_16x16x32_bf16 v[94:97], v[168:171], v[220:223], v[94:97]
	v_mfma_f32_16x16x32_bf16 v[90:93], v[176:179], v[220:223], v[90:93]
	v_mfma_f32_16x16x32_bf16 v[78:81], v[168:171], v[228:231], v[78:81]
	v_mfma_f32_16x16x32_bf16 v[74:77], v[176:179], v[228:231], v[74:77]
	v_mfma_f32_16x16x32_bf16 v[114:117], v[172:175], v[188:191], v[114:117]
	v_mfma_f32_16x16x32_bf16 v[126:129], v[180:183], v[188:191], v[126:129]
	v_mfma_f32_16x16x32_bf16 v[110:113], v[172:175], v[196:199], v[110:113]
	v_mfma_f32_16x16x32_bf16 v[106:109], v[180:183], v[196:199], v[106:109]
	v_mfma_f32_16x16x32_bf16 v[94:97], v[172:175], v[224:227], v[94:97]
	v_mfma_f32_16x16x32_bf16 v[90:93], v[180:183], v[224:227], v[90:93]
	v_mfma_f32_16x16x32_bf16 v[78:81], v[172:175], v[232:235], v[78:81]
	v_mfma_f32_16x16x32_bf16 v[74:77], v[180:183], v[232:235], v[74:77]
	s_barrier
	s_add_i32 s73, s73, s75
	v_lshl_add_u64 v[200:201], vcc, 0, v[0:1]
	s_mov_b32 m0, s73
	ds_read_b128 v[184:187], v167 offset:16384
	ds_read_b128 v[188:191], v167 offset:17408
	ds_read_b128 v[192:195], v167 offset:18432
	ds_read_b128 v[196:199], v167 offset:19456
	ds_read_b128 v[220:223], v167 offset:20480
	ds_read_b128 v[224:227], v167 offset:21504
	ds_read_b128 v[228:231], v167 offset:22528
	ds_read_b128 v[232:235], v167 offset:23552
	global_load_lds_dwordx4 v[200:201], off
	s_add_i32 m0, s73, 0x2000
	v_lshl_add_u64 v[236:237], vcc, 0, v[144:145]
	s_add_u32 vcc_lo, vcc_lo, s46
	s_addc_u32 vcc_hi, vcc_hi, 0
	s_add_i32 s51, s51, s75
	global_load_lds_dwordx4 v[236:237], off
	v_lshl_add_u64 v[238:239], vcc, 0, v[0:1]
	s_mov_b32 m0, s51
	v_lshl_add_u64 v[240:241], vcc, 0, v[144:145]
	global_load_lds_dwordx4 v[238:239], off
	s_add_i32 m0, s51, 0x2000
	v_lshl_add_u64 v[242:243], s[24:25], 0, v[140:141]
	global_load_lds_dwordx4 v[240:241], off
	s_mov_b32 m0, s61
	v_lshl_add_u64 v[244:245], s[24:25], 0, v[142:143]
	global_load_lds_dwordx4 v[242:243], off
	s_mov_b32 m0, s76
	s_nop 0
	global_load_lds_dwordx4 v[244:245], off
	s_waitcnt vmcnt(8)
	s_waitcnt lgkmcnt(0)
	s_barrier
	s_waitcnt lgkmcnt(0)
	v_mfma_f32_16x16x32_bf16 v[54:57], v[130:133], v[184:187], v[54:57]
	v_mfma_f32_16x16x32_bf16 v[50:53], v[150:153], v[184:187], v[50:53]
	v_mfma_f32_16x16x32_bf16 v[42:45], v[130:133], v[192:195], v[42:45]
	v_mfma_f32_16x16x32_bf16 v[38:41], v[150:153], v[192:195], v[38:41]
	v_mfma_f32_16x16x32_bf16 v[30:33], v[130:133], v[220:223], v[30:33]
	v_mfma_f32_16x16x32_bf16 v[26:29], v[150:153], v[220:223], v[26:29]
	v_mfma_f32_16x16x32_bf16 v[14:17], v[130:133], v[228:231], v[14:17]
	v_mfma_f32_16x16x32_bf16 v[10:13], v[150:153], v[228:231], v[10:13]
	v_mfma_f32_16x16x32_bf16 v[54:57], v[134:137], v[188:191], v[54:57]
	v_mfma_f32_16x16x32_bf16 v[50:53], v[154:157], v[188:191], v[50:53]
	v_mfma_f32_16x16x32_bf16 v[42:45], v[134:137], v[196:199], v[42:45]
	v_mfma_f32_16x16x32_bf16 v[38:41], v[154:157], v[196:199], v[38:41]
	v_mfma_f32_16x16x32_bf16 v[30:33], v[134:137], v[224:227], v[30:33]
	v_mfma_f32_16x16x32_bf16 v[26:29], v[154:157], v[224:227], v[26:29]
	v_mfma_f32_16x16x32_bf16 v[14:17], v[134:137], v[232:235], v[14:17]
	v_mfma_f32_16x16x32_bf16 v[10:13], v[154:157], v[232:235], v[10:13]
	v_mfma_f32_16x16x32_bf16 v[62:65], v[168:171], v[184:187], v[62:65]
	v_mfma_f32_16x16x32_bf16 v[58:61], v[176:179], v[184:187], v[58:61]
	v_mfma_f32_16x16x32_bf16 v[46:49], v[168:171], v[192:195], v[46:49]
	v_mfma_f32_16x16x32_bf16 v[34:37], v[176:179], v[192:195], v[34:37]
	v_mfma_f32_16x16x32_bf16 v[22:25], v[168:171], v[220:223], v[22:25]
	v_mfma_f32_16x16x32_bf16 v[18:21], v[176:179], v[220:223], v[18:21]
	v_mfma_f32_16x16x32_bf16 v[6:9], v[168:171], v[228:231], v[6:9]
	v_mfma_f32_16x16x32_bf16 v[2:5], v[176:179], v[228:231], v[2:5]
	v_mfma_f32_16x16x32_bf16 v[62:65], v[172:175], v[188:191], v[62:65]
	v_mfma_f32_16x16x32_bf16 v[58:61], v[180:183], v[188:191], v[58:61]
	v_mfma_f32_16x16x32_bf16 v[46:49], v[172:175], v[196:199], v[46:49]
	v_mfma_f32_16x16x32_bf16 v[34:37], v[180:183], v[196:199], v[34:37]
	v_mfma_f32_16x16x32_bf16 v[22:25], v[172:175], v[224:227], v[22:25]
	v_mfma_f32_16x16x32_bf16 v[18:21], v[180:183], v[224:227], v[18:21]
	v_mfma_f32_16x16x32_bf16 v[6:9], v[172:175], v[232:235], v[6:9]
	v_mfma_f32_16x16x32_bf16 v[2:5], v[180:183], v[232:235], v[2:5]
	s_barrier
	s_add_i32 s51, 0, 0x18000
	s_add_i32 s73, 0, 0x1c000
	v_add_u32_e32 v154, s51, v162
	v_add_u32_e32 v180, s73, v162
	ds_read_b128 v[130:133], v154
	ds_read_b128 v[134:137], v154 offset:1024
	ds_read_b128 v[150:153], v154 offset:2048
	ds_read_b128 v[154:157], v154 offset:3072
	ds_read_b128 v[168:171], v180
	ds_read_b128 v[172:175], v180 offset:1024
	ds_read_b128 v[176:179], v180 offset:2048
	ds_read_b128 v[180:183], v180 offset:3072
	s_add_u32 s24, s24, s46
	s_addc_u32 s25, s25, 0
	s_mov_b32 m0, s77
	v_lshl_add_u64 v[246:247], s[24:25], 0, v[140:141]
	ds_read_b128 v[184:187], v167 offset:32768
	ds_read_b128 v[188:191], v167 offset:33792
	ds_read_b128 v[192:195], v167 offset:34816
	ds_read_b128 v[196:199], v167 offset:35840
	ds_read_b128 v[220:223], v167 offset:36864
	ds_read_b128 v[224:227], v167 offset:37888
	ds_read_b128 v[228:231], v167 offset:38912
	ds_read_b128 v[232:235], v167 offset:39936
	global_load_lds_dwordx4 v[246:247], off
	v_lshl_add_u64 v[246:247], s[24:25], 0, v[142:143]
	s_mov_b32 m0, s28
	s_nop 0
	global_load_lds_dwordx4 v[246:247], off
	s_waitcnt vmcnt(8)
	s_waitcnt lgkmcnt(0)
	s_barrier
	s_waitcnt lgkmcnt(0)
	v_mfma_f32_16x16x32_bf16 v[122:125], v[130:133], v[184:187], v[122:125]
	v_mfma_f32_16x16x32_bf16 v[118:121], v[150:153], v[184:187], v[118:121]
	v_mfma_f32_16x16x32_bf16 v[102:105], v[130:133], v[192:195], v[102:105]
	v_mfma_f32_16x16x32_bf16 v[98:101], v[150:153], v[192:195], v[98:101]
	v_mfma_f32_16x16x32_bf16 v[86:89], v[130:133], v[220:223], v[86:89]
	v_mfma_f32_16x16x32_bf16 v[82:85], v[150:153], v[220:223], v[82:85]
	v_mfma_f32_16x16x32_bf16 v[70:73], v[130:133], v[228:231], v[70:73]
	v_mfma_f32_16x16x32_bf16 v[66:69], v[150:153], v[228:231], v[66:69]
	v_mfma_f32_16x16x32_bf16 v[122:125], v[134:137], v[188:191], v[122:125]
	v_mfma_f32_16x16x32_bf16 v[118:121], v[154:157], v[188:191], v[118:121]
	v_mfma_f32_16x16x32_bf16 v[102:105], v[134:137], v[196:199], v[102:105]
	v_mfma_f32_16x16x32_bf16 v[98:101], v[154:157], v[196:199], v[98:101]
	v_mfma_f32_16x16x32_bf16 v[86:89], v[134:137], v[224:227], v[86:89]
	v_mfma_f32_16x16x32_bf16 v[82:85], v[154:157], v[224:227], v[82:85]
	v_mfma_f32_16x16x32_bf16 v[70:73], v[134:137], v[232:235], v[70:73]
	v_mfma_f32_16x16x32_bf16 v[66:69], v[154:157], v[232:235], v[66:69]
	v_mfma_f32_16x16x32_bf16 v[114:117], v[168:171], v[184:187], v[114:117]
	v_mfma_f32_16x16x32_bf16 v[126:129], v[176:179], v[184:187], v[126:129]
	v_mfma_f32_16x16x32_bf16 v[110:113], v[168:171], v[192:195], v[110:113]
	v_mfma_f32_16x16x32_bf16 v[106:109], v[176:179], v[192:195], v[106:109]
	v_mfma_f32_16x16x32_bf16 v[94:97], v[168:171], v[220:223], v[94:97]
	v_mfma_f32_16x16x32_bf16 v[90:93], v[176:179], v[220:223], v[90:93]
	v_mfma_f32_16x16x32_bf16 v[78:81], v[168:171], v[228:231], v[78:81]
	v_mfma_f32_16x16x32_bf16 v[74:77], v[176:179], v[228:231], v[74:77]
	v_mfma_f32_16x16x32_bf16 v[114:117], v[172:175], v[188:191], v[114:117]
	v_mfma_f32_16x16x32_bf16 v[126:129], v[180:183], v[188:191], v[126:129]
	v_mfma_f32_16x16x32_bf16 v[110:113], v[172:175], v[196:199], v[110:113]
	v_mfma_f32_16x16x32_bf16 v[106:109], v[180:183], v[196:199], v[106:109]
	v_mfma_f32_16x16x32_bf16 v[94:97], v[172:175], v[224:227], v[94:97]
	v_mfma_f32_16x16x32_bf16 v[90:93], v[180:183], v[224:227], v[90:93]
	v_mfma_f32_16x16x32_bf16 v[78:81], v[172:175], v[232:235], v[78:81]
	v_mfma_f32_16x16x32_bf16 v[74:77], v[180:183], v[232:235], v[74:77]
	s_barrier
	s_add_i32 s24, s51, s75
	v_lshl_add_u64 v[200:201], v[200:201], 0, s[64:65]
	s_mov_b32 m0, s24
	ds_read_b128 v[184:187], v167 offset:49152
	ds_read_b128 v[188:191], v167 offset:50176
	ds_read_b128 v[192:195], v167 offset:51200
	ds_read_b128 v[196:199], v167 offset:52224
	ds_read_b128 v[220:223], v167 offset:53248
	ds_read_b128 v[224:227], v167 offset:54272
	ds_read_b128 v[228:231], v167 offset:55296
	ds_read_b128 v[232:235], v167 offset:56320
	global_load_lds_dwordx4 v[200:201], off
	v_lshl_add_u64 v[200:201], v[236:237], 0, s[64:65]
	s_add_i32 m0, s24, 0x2000
	s_add_i32 s24, s73, s75
	global_load_lds_dwordx4 v[200:201], off
	v_lshl_add_u64 v[200:201], v[238:239], 0, s[64:65]
	s_mov_b32 m0, s24
	s_nop 0
	global_load_lds_dwordx4 v[200:201], off
	v_lshl_add_u64 v[200:201], v[240:241], 0, s[64:65]
	s_add_i32 m0, s24, 0x2000
	s_nop 0
	global_load_lds_dwordx4 v[200:201], off
	v_lshl_add_u64 v[200:201], v[242:243], 0, s[64:65]
	s_mov_b32 m0, s29
	s_nop 0
	global_load_lds_dwordx4 v[200:201], off
	v_lshl_add_u64 v[200:201], v[244:245], 0, s[64:65]
	s_mov_b32 m0, s19
	s_nop 0
	global_load_lds_dwordx4 v[200:201], off
	s_waitcnt vmcnt(8)
	s_waitcnt lgkmcnt(0)
	s_barrier
	s_waitcnt lgkmcnt(0)
	v_mfma_f32_16x16x32_bf16 v[54:57], v[130:133], v[184:187], v[54:57]
	v_mfma_f32_16x16x32_bf16 v[50:53], v[150:153], v[184:187], v[50:53]
	v_mfma_f32_16x16x32_bf16 v[42:45], v[130:133], v[192:195], v[42:45]
	v_mfma_f32_16x16x32_bf16 v[38:41], v[150:153], v[192:195], v[38:41]
	v_mfma_f32_16x16x32_bf16 v[30:33], v[130:133], v[220:223], v[30:33]
	v_mfma_f32_16x16x32_bf16 v[26:29], v[150:153], v[220:223], v[26:29]
	v_mfma_f32_16x16x32_bf16 v[14:17], v[130:133], v[228:231], v[14:17]
	v_mfma_f32_16x16x32_bf16 v[10:13], v[150:153], v[228:231], v[10:13]
	v_mfma_f32_16x16x32_bf16 v[54:57], v[134:137], v[188:191], v[54:57]
	v_mfma_f32_16x16x32_bf16 v[50:53], v[154:157], v[188:191], v[50:53]
	v_mfma_f32_16x16x32_bf16 v[42:45], v[134:137], v[196:199], v[42:45]
	v_mfma_f32_16x16x32_bf16 v[38:41], v[154:157], v[196:199], v[38:41]
	v_mfma_f32_16x16x32_bf16 v[30:33], v[134:137], v[224:227], v[30:33]
	v_mfma_f32_16x16x32_bf16 v[26:29], v[154:157], v[224:227], v[26:29]
	v_mfma_f32_16x16x32_bf16 v[14:17], v[134:137], v[232:235], v[14:17]
	v_mfma_f32_16x16x32_bf16 v[10:13], v[154:157], v[232:235], v[10:13]
	v_mfma_f32_16x16x32_bf16 v[62:65], v[168:171], v[184:187], v[62:65]
	v_mfma_f32_16x16x32_bf16 v[58:61], v[176:179], v[184:187], v[58:61]
	v_mfma_f32_16x16x32_bf16 v[46:49], v[168:171], v[192:195], v[46:49]
	v_mfma_f32_16x16x32_bf16 v[34:37], v[176:179], v[192:195], v[34:37]
	v_mfma_f32_16x16x32_bf16 v[22:25], v[168:171], v[220:223], v[22:25]
	v_mfma_f32_16x16x32_bf16 v[18:21], v[176:179], v[220:223], v[18:21]
	v_mfma_f32_16x16x32_bf16 v[6:9], v[168:171], v[228:231], v[6:9]
	v_mfma_f32_16x16x32_bf16 v[2:5], v[176:179], v[228:231], v[2:5]
	v_mfma_f32_16x16x32_bf16 v[62:65], v[172:175], v[188:191], v[62:65]
	v_mfma_f32_16x16x32_bf16 v[58:61], v[180:183], v[188:191], v[58:61]
	v_mfma_f32_16x16x32_bf16 v[46:49], v[172:175], v[196:199], v[46:49]
	v_mfma_f32_16x16x32_bf16 v[34:37], v[180:183], v[196:199], v[34:37]
	v_mfma_f32_16x16x32_bf16 v[22:25], v[172:175], v[224:227], v[22:25]
	v_mfma_f32_16x16x32_bf16 v[18:21], v[180:183], v[224:227], v[18:21]
	v_mfma_f32_16x16x32_bf16 v[6:9], v[172:175], v[232:235], v[6:9]
	v_mfma_f32_16x16x32_bf16 v[2:5], v[180:183], v[232:235], v[2:5]
	s_barrier
	s_add_u32 s11, s11, 0x100
	s_addc_u32 s71, s71, 0
	s_add_u32 s2, s2, 0x100
	s_addc_u32 s3, s3, 0
	s_cmp_ge_u32 s72, s78
	s_mov_b32 s51, s72
	s_cbranch_scc0 .LBB0_2002
	s_setprio 0
	s_and_b64 vcc, exec, s[68:69]
	s_cbranch_vccz .LBB0_2005
